# early buffer_wbl2 at 50, 75, 87.5 percent and n-1 arrivals per XCD
# baseline (speedup 1.0000x reference)
; __device__ __forceinline__ unsigned xb_ld(unsigned* p)              { return __hip_atomic_load(p, __ATOMIC_RELAXED, __HIP_MEMORY_SCOPE_AGENT); }
; __device__ __forceinline__ unsigned xb_add(unsigned* p, unsigned v) { return __hip_atomic_fetch_add(p, v, __ATOMIC_RELAXED, __HIP_MEMORY_SCOPE_AGENT); }
; #define XB_SPIN(cond, bar) do { unsigned _sp = 0; while (cond) { __builtin_amdgcn_s_sleep(0); \
;     if ((++_sp & 255u) == 0u) { if (xb_ld(&(bar)[XB_TMO])) break; if (_sp > XB_SPIN_CAP) { atomicAdd(&(bar)[XB_TMO], 1u); break; } } } } while (0)
; __device__ __forceinline__ void xcd_barrier(const XcdBarrier& b) {
;     ...
;         const unsigned old = xb_add(&bar[XB_XSUB(b.x)], 1u);
;         const unsigned gen = old / nloc;
;         if (old + 1u == (gen + 1u) * nloc) {
;             __builtin_amdgcn_fence(__ATOMIC_RELEASE, "agent");
;     ...
;             XB_SPIN(xb_ld(&bar[XB_XGEN(b.x)]) == gen, bar);
.LBB0_155:
	s_or_b64 exec, exec, s[0:1]
	v_cvt_f32_u32_e32 v4, v2
	s_waitcnt vmcnt(0)
	v_readfirstlane_b32 s0, v3
	v_sub_u32_e32 v3, 0, v2
	v_rcp_iflag_f32_e32 v4, v4
	v_add_u32_e32 v5, s0, v1
	v_mul_f32_e32 v4, 0x4f7ffffe, v4
	v_cvt_u32_f32_e32 v4, v4
	v_mul_lo_u32 v1, v3, v4
	v_mul_hi_u32 v1, v4, v1
	v_add_u32_e32 v1, v4, v1
	v_mul_hi_u32 v1, v5, v1
	v_mul_lo_u32 v3, v1, v2
	v_sub_u32_e32 v3, v5, v3
	v_add_u32_e32 v4, 1, v1
	v_cmp_ge_u32_e32 vcc, v3, v2
	s_nop 1
	v_cndmask_b32_e32 v1, v1, v4, vcc
	v_sub_u32_e32 v4, v3, v2
	v_cndmask_b32_e32 v3, v3, v4, vcc
	v_add_u32_e32 v4, 1, v1
	v_cmp_ge_u32_e32 vcc, v3, v2
	v_add_u32_e32 v3, 1, v5
	s_nop 0
	v_cndmask_b32_e32 v1, v1, v4, vcc
	v_mul_lo_u32 v4, v2, v1
	v_add_u32_e32 v2, v4, v2
	v_cmp_ne_u32_e32 vcc, v3, v2
	s_and_saveexec_b64 s[0:1], vcc
	s_xor_b64 s[0:1], exec, s[0:1]
	s_cbranch_execz .LBB0_169
	v_readlane_b32 s2, v252, 7
	v_readlane_b32 s3, v252, 8
	s_waitcnt lgkmcnt(0)
	v_mad_u32_u24 v1, v0, v1, v0
	v_sub_u32_e32 v3, v3, v4
	v_sub_u32_e32 v4, v2, v4
	v_lshlrev_b32_e32 v5, 1, v3
	v_cmp_eq_u32_e32 vcc, v5, v4
	s_cbranch_vccnz .Lewb_do0
	v_lshlrev_b32_e32 v5, 2, v3
	v_mul_u32_u24_e32 v0, 3, v4
	v_cmp_eq_u32_e32 vcc, v5, v0
	s_cbranch_vccnz .Lewb_do0
	v_lshlrev_b32_e32 v5, 3, v3
	v_mul_u32_u24_e32 v0, 7, v4
	v_cmp_eq_u32_e32 vcc, v5, v0
	s_cbranch_vccnz .Lewb_do0
	v_add_u32_e32 v5, 1, v3
	v_cmp_eq_u32_e32 vcc, v5, v4
	s_cbranch_vccz .Lewb_skip0
.Lewb_do0:
	buffer_wbl2 sc1
